# scan gate blocks: skip the valid-lane masking when the whole wave is valid (scalar test)
# baseline (speedup 1.0000x reference)
; #define LAS __attribute__((address_space(3)))
; __device__ __forceinline__ unsigned cvt_pk(float lo, float hi) { unsigned r; asm("v_cvt_pk_bf16_f32 %0, %1, %2" : "=v"(r) : "v"(lo), "v"(hi)); return r; }
; __device__ __forceinline__ float bflo(unsigned w) { return __uint_as_float(w << 16); }
; __device__ __forceinline__ float bfhi(unsigned w) { return __uint_as_float(w & 0xffff0000u); }
; #define MFMA16(a, b, c) __builtin_amdgcn_mfma_f32_16x16x32_bf16((a), (b), (c), 0, 0, 0)
; template <int DIR>
; __device__ __forceinline__ void rnn_scan_unit(const Params& p, LAS unsigned char* lds, int b, int g) {
;     ...
;         { const int tl0 = lane >> 3, c8 = lane & 7;
; #pragma unroll
;           for (int hh = 0; hh < 2; ++hh) { const int tl = tl0 + 8 * hh;
;               f32x4 o0 = cbv[0], o1 = cbv[1];
; #pragma unroll
;               for (int j = 0; j < 4; ++j) { const u32x4 xw_ = *(const LAS u32x4*)(xrb + (tl + j) * 64 + 8 * c8);
;                   o0[0] += cwv[j][0][0] * bflo(xw_.x); o0[1] += cwv[j][0][1] * bfhi(xw_.x); o0[2] += cwv[j][0][2] * bflo(xw_.y); o0[3] += cwv[j][0][3] * bfhi(xw_.y);
;                   o1[0] += cwv[j][1][0] * bflo(xw_.z); o1[1] += cwv[j][1][1] * bfhi(xw_.z); o1[2] += cwv[j][1][2] * bflo(xw_.w); o1[3] += cwv[j][1][3] * bfhi(xw_.w); }
;               *(LAS f32x4*)(xcf + tl * XS + 8 * c8) = o0; *(LAS f32x4*)(xcf + tl * XS + 8 * c8 + 4) = o1; } }
;         asm volatile("s_waitcnt lgkmcnt(0)" ::: "memory");
;         { const int tt = fr; const bool valid = (t0 + tt) < TT;
;           bf16x8 af[2];
; #pragma unroll
;           for (int ks = 0; ks < 2; ++ks) { const f32x4 x0 = *(const LAS f32x4*)(xcf + tt * XS + 32 * ks + 8 * fq), x1 = *(const LAS f32x4*)(xcf + tt * XS + 32 * ks + 8 * fq + 4);
;               u32x4 w; w.x = cvt_pk(x0[0], x0[1]); w.y = cvt_pk(x0[2], x0[3]); w.z = cvt_pk(x1[0], x1[1]); w.w = cvt_pk(x1[2], x1[3]); af[ks] = __builtin_bit_cast(bf16x8, w); }
; #pragma unroll
;           for (int n = 0; n < 4; ++n) { const int c4 = 16 * n + 4 * fq;
;               f32x4 ra = *(const LAS f32x4*)(cst + c4), ia = *(const LAS f32x4*)(cst + 64 + c4);
; #pragma unroll
;               for (int ks = 0; ks < 2; ++ks) { ra = MFMA16(wreg[(0 * 4 + n) * 2 + ks], af[ks], ra); ia = MFMA16(wl[((1 * 4 + n) * 2 + ks) * 64 + lane], af[ks], ia); }
.LBB0_550:
	v_add_u32_e32 v0, v123, v125
	ds_read_b128 v[88:91], v0
	ds_read_b128 v[92:95], v0 offset:128
	ds_read_b128 v[96:99], v0 offset:256
	ds_read_b128 v[100:103], v0 offset:384
	v_mov_b32_e32 v113, 0
	s_waitcnt lgkmcnt(3)
	v_lshlrev_b32_e32 v104, 16, v88
	v_and_b32_e32 v105, 0xffff0000, v88
	v_lshlrev_b32_e32 v88, 16, v89
	v_and_b32_e32 v89, 0xffff0000, v89
	v_pk_fma_f32 v[104:105], v[36:37], v[104:105], v[40:41]
	s_waitcnt lgkmcnt(2)
	v_lshlrev_b32_e32 v106, 16, v92
	v_and_b32_e32 v107, 0xffff0000, v92
	v_pk_fma_f32 v[88:89], v[38:39], v[88:89], v[42:43]
	v_lshlrev_b32_e32 v92, 16, v93
	v_and_b32_e32 v93, 0xffff0000, v93
	v_pk_fma_f32 v[104:105], v[8:9], v[106:107], v[104:105]
	s_waitcnt lgkmcnt(1)
	v_lshlrev_b32_e32 v106, 16, v96
	v_and_b32_e32 v107, 0xffff0000, v96
	v_pk_fma_f32 v[88:89], v[10:11], v[92:93], v[88:89]
	v_lshlrev_b32_e32 v92, 16, v97
	v_and_b32_e32 v93, 0xffff0000, v97
	v_pk_fma_f32 v[104:105], v[12:13], v[106:107], v[104:105]
	s_waitcnt lgkmcnt(0)
	v_lshlrev_b32_e32 v106, 16, v100
	v_and_b32_e32 v107, 0xffff0000, v100
	v_pk_fma_f32 v[88:89], v[14:15], v[92:93], v[88:89]
	v_lshlrev_b32_e32 v92, 16, v101
	v_and_b32_e32 v93, 0xffff0000, v101
	v_pk_fma_f32 v[104:105], v[20:21], v[106:107], v[104:105]
	v_pk_fma_f32 v[106:107], v[22:23], v[92:93], v[88:89]
	v_lshlrev_b32_e32 v88, 16, v90
	v_and_b32_e32 v89, 0xffff0000, v90
	v_pk_fma_f32 v[88:89], v[28:29], v[88:89], v[32:33]
	v_lshlrev_b32_e32 v92, 16, v94
	v_and_b32_e32 v93, 0xffff0000, v94
	v_pk_fma_f32 v[88:89], v[4:5], v[92:93], v[88:89]
	v_lshlrev_b32_e32 v92, 16, v98
	v_and_b32_e32 v93, 0xffff0000, v98
	v_pk_fma_f32 v[88:89], v[16:17], v[92:93], v[88:89]
	v_lshlrev_b32_e32 v92, 16, v102
	v_and_b32_e32 v93, 0xffff0000, v102
	v_lshlrev_b32_e32 v90, 16, v91
	v_and_b32_e32 v91, 0xffff0000, v91
	v_pk_fma_f32 v[88:89], v[24:25], v[92:93], v[88:89]
	v_pk_fma_f32 v[90:91], v[30:31], v[90:91], v[34:35]
	v_lshlrev_b32_e32 v92, 16, v95
	v_and_b32_e32 v93, 0xffff0000, v95
	v_pk_fma_f32 v[90:91], v[6:7], v[92:93], v[90:91]
	v_lshlrev_b32_e32 v92, 16, v99
	v_and_b32_e32 v93, 0xffff0000, v99
	v_pk_fma_f32 v[90:91], v[18:19], v[92:93], v[90:91]
	v_lshlrev_b32_e32 v92, 16, v103
	v_and_b32_e32 v93, 0xffff0000, v103
	v_pk_fma_f32 v[90:91], v[26:27], v[92:93], v[90:91]
	ds_write_b128 v166, v[104:107] offset:2432
	ds_write_b128 v166, v[88:91] offset:2448
	ds_read_b128 v[88:91], v167
	ds_read_b128 v[92:95], v0 offset:1152
	ds_read_b128 v[96:99], v0 offset:1280
	ds_read_b128 v[100:103], v0 offset:1408
	v_add_u32_e32 v0, s19, v160
	s_waitcnt lgkmcnt(3)
	v_lshlrev_b32_e32 v104, 16, v88
	v_and_b32_e32 v105, 0xffff0000, v88
	v_lshlrev_b32_e32 v88, 16, v89
	v_and_b32_e32 v89, 0xffff0000, v89
	v_pk_fma_f32 v[104:105], v[36:37], v[104:105], v[40:41]
	s_waitcnt lgkmcnt(2)
	v_lshlrev_b32_e32 v106, 16, v92
	v_and_b32_e32 v107, 0xffff0000, v92
	v_pk_fma_f32 v[88:89], v[38:39], v[88:89], v[42:43]
	v_lshlrev_b32_e32 v92, 16, v93
	v_and_b32_e32 v93, 0xffff0000, v93
	v_pk_fma_f32 v[104:105], v[8:9], v[106:107], v[104:105]
	s_waitcnt lgkmcnt(1)
	v_lshlrev_b32_e32 v106, 16, v96
	v_and_b32_e32 v107, 0xffff0000, v96
	v_pk_fma_f32 v[88:89], v[10:11], v[92:93], v[88:89]
	v_lshlrev_b32_e32 v92, 16, v97
	v_and_b32_e32 v93, 0xffff0000, v97
	v_pk_fma_f32 v[104:105], v[12:13], v[106:107], v[104:105]
	s_waitcnt lgkmcnt(0)
	v_lshlrev_b32_e32 v106, 16, v100
	v_and_b32_e32 v107, 0xffff0000, v100
	v_pk_fma_f32 v[88:89], v[14:15], v[92:93], v[88:89]
	v_lshlrev_b32_e32 v92, 16, v101
	v_and_b32_e32 v93, 0xffff0000, v101
	v_pk_fma_f32 v[104:105], v[20:21], v[106:107], v[104:105]
	v_pk_fma_f32 v[106:107], v[22:23], v[92:93], v[88:89]
	v_lshlrev_b32_e32 v88, 16, v90
	v_and_b32_e32 v89, 0xffff0000, v90
	v_pk_fma_f32 v[88:89], v[28:29], v[88:89], v[32:33]
	v_lshlrev_b32_e32 v92, 16, v94
	v_and_b32_e32 v93, 0xffff0000, v94
	v_pk_fma_f32 v[88:89], v[4:5], v[92:93], v[88:89]
	v_lshlrev_b32_e32 v92, 16, v98
	v_and_b32_e32 v93, 0xffff0000, v98
	v_pk_fma_f32 v[88:89], v[16:17], v[92:93], v[88:89]
	v_lshlrev_b32_e32 v92, 16, v102
	v_and_b32_e32 v93, 0xffff0000, v102
	v_lshlrev_b32_e32 v90, 16, v91
	v_and_b32_e32 v91, 0xffff0000, v91
	v_pk_fma_f32 v[88:89], v[24:25], v[92:93], v[88:89]
	v_pk_fma_f32 v[90:91], v[30:31], v[90:91], v[34:35]
	v_lshlrev_b32_e32 v92, 16, v95
	v_and_b32_e32 v93, 0xffff0000, v95
	v_pk_fma_f32 v[90:91], v[6:7], v[92:93], v[90:91]
	v_lshlrev_b32_e32 v92, 16, v99
	v_and_b32_e32 v93, 0xffff0000, v99
	v_pk_fma_f32 v[90:91], v[18:19], v[92:93], v[90:91]
	v_lshlrev_b32_e32 v92, 16, v103
	v_and_b32_e32 v93, 0xffff0000, v103
	v_pk_fma_f32 v[90:91], v[26:27], v[92:93], v[90:91]
	ds_write_b128 v166, v[104:107] offset:4608
	ds_write_b128 v166, v[88:91] offset:4624
	s_waitcnt lgkmcnt(0)
	ds_read_b128 v[88:91], v168 offset:2432
	ds_read_b128 v[92:95], v168 offset:2448
	s_waitcnt lgkmcnt(1)
	v_cvt_pk_bf16_f32 v88, v88, v89
	v_cvt_pk_bf16_f32 v89, v90, v91
	s_waitcnt lgkmcnt(0)
	v_cvt_pk_bf16_f32 v90, v92, v93
	v_cvt_pk_bf16_f32 v91, v94, v95
	ds_read_b128 v[92:95], v168 offset:2560
	ds_read_b128 v[96:99], v168 offset:2576
	s_waitcnt lgkmcnt(1)
	v_cvt_pk_bf16_f32 v92, v92, v93
	v_cvt_pk_bf16_f32 v93, v94, v95
	s_waitcnt lgkmcnt(0)
	v_cvt_pk_bf16_f32 v94, v96, v97
	v_cvt_pk_bf16_f32 v95, v98, v99
	ds_read_b128 v[96:99], v126
	ds_read_b128 v[100:103], v127
	ds_read_b128 v[104:107], v117 offset:8192
	s_waitcnt lgkmcnt(2)
	v_mfma_f32_16x16x32_bf16 v[96:99], v[44:47], v[88:91], v[96:99]
	v_cmp_gt_i32_e64 s[16:17], s86, v0
	v_mov_b32_e32 v112, 0
	s_waitcnt lgkmcnt(0)
	v_mfma_f32_16x16x32_bf16 v[100:103], v[104:107], v[88:91], v[100:103]
	v_mfma_f32_16x16x32_bf16 v[104:107], v[48:51], v[92:95], v[96:99]
	s_nop 2
	ds_read_b128 v[96:99], v117 offset:9216
	s_waitcnt lgkmcnt(0)
; #define LAS __attribute__((address_space(3)))
; #define MFMA16(a, b, c) __builtin_amdgcn_mfma_f32_16x16x32_bf16((a), (b), (c), 0, 0, 0)
; template <int DIR>
; __device__ __forceinline__ void rnn_scan_unit(const Params& p, LAS unsigned char* lds, int b, int g) {
;     ...
;           for (int n = 0; n < 4; ++n) { const int c4 = 16 * n + 4 * fq;
;               f32x4 ra = *(const LAS f32x4*)(cst + c4), ia = *(const LAS f32x4*)(cst + 64 + c4);
; #pragma unroll
;               for (int ks = 0; ks < 2; ++ks) { ra = MFMA16(wreg[(0 * 4 + n) * 2 + ks], af[ks], ra); ia = MFMA16(wl[((1 * 4 + n) * 2 + ks) * 64 + lane], af[ks], ia); }
;               const f32x4 xv = *(const LAS f32x4*)(xcf + tt * XS + c4);
;               const f32x4 spv = *(const LAS f32x4*)(cst + 128 + c4);
;               f32x4 av, bv;
; #pragma unroll
;               for (int i = 0; i < 4; ++i) { const float r = __builtin_amdgcn_rcpf(1.0f + __builtin_amdgcn_exp2f(ra[i])), ig = __builtin_amdgcn_rcpf(1.0f + __builtin_amdgcn_exp2f(ia[i]));
;                   const float a = __builtin_amdgcn_exp2f(r * spv[i]); const float em = fmaf(-a, a, 1.0f);
;                   av[i] = valid ? a : 1.0f; bv[i] = valid ? __builtin_amdgcn_sqrtf(fmaxf(em, 0.0f)) * ig * xv[i] : 0.0f; }
;               *(LAS f32x4*)(al + tt * 64 + c4) = av; *(LAS f32x4*)(bl + tt * 64 + c4) = bv; } }
	v_mfma_f32_16x16x32_bf16 v[100:103], v[96:99], v[92:95], v[100:103]
	s_nop 1
	ds_read_b128 v[96:99], v128 offset:2432
	ds_read_b128 v[108:111], v129
	v_exp_f32_e32 v104, v104
	v_exp_f32_e32 v105, v105
	v_exp_f32_e32 v106, v106
	v_exp_f32_e32 v107, v107
	v_exp_f32_e32 v100, v100
	v_exp_f32_e32 v101, v101
	v_exp_f32_e32 v102, v102
	v_exp_f32_e32 v103, v103
	v_add_f32_e32 v104, 1.0, v104
	v_add_f32_e32 v105, 1.0, v105
	v_add_f32_e32 v106, 1.0, v106
	v_add_f32_e32 v107, 1.0, v107
	v_add_f32_e32 v100, 1.0, v100
	v_add_f32_e32 v101, 1.0, v101
	v_add_f32_e32 v102, 1.0, v102
	v_add_f32_e32 v103, 1.0, v103
	v_rcp_f32_e32 v104, v104
	v_rcp_f32_e32 v105, v105
	v_rcp_f32_e32 v106, v106
	v_rcp_f32_e32 v107, v107
	v_rcp_f32_e32 v100, v100
	v_rcp_f32_e32 v101, v101
	v_rcp_f32_e32 v102, v102
	v_rcp_f32_e32 v103, v103
	s_waitcnt lgkmcnt(0)
	v_mul_f32_e32 v104, v104, v108
	v_mul_f32_e32 v105, v105, v109
	v_mul_f32_e32 v106, v106, v110
	v_mul_f32_e32 v107, v107, v111
	v_exp_f32_e32 v104, v104
	v_exp_f32_e32 v105, v105
	v_exp_f32_e32 v106, v106
	v_exp_f32_e32 v107, v107
	v_fma_f32 v112, -v104, v104, 1.0
	v_fma_f32 v113, -v105, v105, 1.0
	v_fma_f32 v114, -v106, v106, 1.0
	v_fma_f32 v115, -v107, v107, 1.0
	v_max_f32_e32 v112, 0, v112
	v_max_f32_e32 v113, 0, v113
	v_max_f32_e32 v114, 0, v114
	v_max_f32_e32 v115, 0, v115
	v_sqrt_f32_e32 v112, v112
	v_sqrt_f32_e32 v113, v113
	v_sqrt_f32_e32 v114, v114
	v_sqrt_f32_e32 v115, v115
	v_mul_f32_e32 v100, v100, v112
	v_mul_f32_e32 v101, v101, v113
	v_mul_f32_e32 v102, v102, v114
	v_mul_f32_e32 v103, v103, v115
	v_mul_f32_e32 v112, v96, v100
	v_mul_f32_e32 v113, v97, v101
	v_mul_f32_e32 v114, v98, v102
	v_mul_f32_e32 v115, v99, v103
	s_cmp_eq_u64 s[16:17], exec
	s_cbranch_scc1 .Lgate_nomask_7
	v_cndmask_b32_e64 v112, 0, v112, s[16:17]
	v_cndmask_b32_e64 v113, 0, v113, s[16:17]
	v_cndmask_b32_e64 v114, 0, v114, s[16:17]
	v_cndmask_b32_e64 v115, 0, v115, s[16:17]
	v_cndmask_b32_e64 v104, 1.0, v104, s[16:17]
	v_cndmask_b32_e64 v105, 1.0, v105, s[16:17]
	v_cndmask_b32_e64 v106, 1.0, v106, s[16:17]
	v_cndmask_b32_e64 v107, 1.0, v107, s[16:17]
.Lgate_nomask_7:
	ds_write_b128 v130, v[104:107] offset:6784
	ds_write_b128 v130, v[112:115] offset:10880
	ds_read_b128 v[96:99], v131
	ds_read_b128 v[100:103], v132
	ds_read_b128 v[104:107], v117 offset:10240
	s_waitcnt lgkmcnt(2)
	v_mfma_f32_16x16x32_bf16 v[96:99], v[52:55], v[88:91], v[96:99]
	v_mov_b32_e32 v113, 0
	v_mov_b32_e32 v112, 0
	s_waitcnt lgkmcnt(0)
	v_mfma_f32_16x16x32_bf16 v[100:103], v[104:107], v[88:91], v[100:103]
	v_mfma_f32_16x16x32_bf16 v[104:107], v[56:59], v[92:95], v[96:99]
	s_nop 2
	ds_read_b128 v[96:99], v117 offset:11264
	s_waitcnt lgkmcnt(0)
	v_mfma_f32_16x16x32_bf16 v[96:99], v[96:99], v[92:95], v[100:103]
	s_nop 1
	ds_read_b128 v[100:103], v128 offset:2496
	ds_read_b128 v[108:111], v133
	v_exp_f32_e32 v104, v104
	v_exp_f32_e32 v105, v105
	v_exp_f32_e32 v106, v106
	v_exp_f32_e32 v107, v107
	v_exp_f32_e32 v96, v96
	v_exp_f32_e32 v97, v97
	v_exp_f32_e32 v98, v98
	v_exp_f32_e32 v99, v99
	v_add_f32_e32 v104, 1.0, v104
	v_add_f32_e32 v105, 1.0, v105
	v_add_f32_e32 v106, 1.0, v106
	v_add_f32_e32 v107, 1.0, v107
	v_add_f32_e32 v96, 1.0, v96
	v_add_f32_e32 v97, 1.0, v97
	v_add_f32_e32 v98, 1.0, v98
	v_add_f32_e32 v99, 1.0, v99
	v_rcp_f32_e32 v104, v104
	v_rcp_f32_e32 v105, v105
	v_rcp_f32_e32 v106, v106
	v_rcp_f32_e32 v107, v107
	v_rcp_f32_e32 v96, v96
	v_rcp_f32_e32 v97, v97
	v_rcp_f32_e32 v98, v98
	v_rcp_f32_e32 v99, v99
	s_waitcnt lgkmcnt(0)
	v_mul_f32_e32 v104, v104, v108
	v_mul_f32_e32 v105, v105, v109
	v_mul_f32_e32 v106, v106, v110
	v_mul_f32_e32 v107, v107, v111
	v_exp_f32_e32 v104, v104
	v_exp_f32_e32 v105, v105
	v_exp_f32_e32 v106, v106
	v_exp_f32_e32 v107, v107
	v_fma_f32 v112, -v104, v104, 1.0
	v_fma_f32 v113, -v105, v105, 1.0
	v_fma_f32 v114, -v106, v106, 1.0
	v_fma_f32 v115, -v107, v107, 1.0
	v_max_f32_e32 v112, 0, v112
	v_max_f32_e32 v113, 0, v113
	v_max_f32_e32 v114, 0, v114
	v_max_f32_e32 v115, 0, v115
	v_sqrt_f32_e32 v112, v112
	v_sqrt_f32_e32 v113, v113
	v_sqrt_f32_e32 v114, v114
	v_sqrt_f32_e32 v115, v115
	v_mul_f32_e32 v96, v96, v112
	v_mul_f32_e32 v97, v97, v113
	v_mul_f32_e32 v98, v98, v114
	v_mul_f32_e32 v99, v99, v115
	v_mul_f32_e32 v112, v100, v96
	v_mul_f32_e32 v113, v101, v97
	v_mul_f32_e32 v114, v102, v98
	v_mul_f32_e32 v115, v103, v99
	s_cmp_eq_u64 s[16:17], exec
	s_cbranch_scc1 .Lgate_nomask_6
	v_cndmask_b32_e64 v112, 0, v112, s[16:17]
	v_cndmask_b32_e64 v113, 0, v113, s[16:17]
	v_cndmask_b32_e64 v114, 0, v114, s[16:17]
	v_cndmask_b32_e64 v115, 0, v115, s[16:17]
	v_cndmask_b32_e64 v104, 1.0, v104, s[16:17]
	v_cndmask_b32_e64 v105, 1.0, v105, s[16:17]
	v_cndmask_b32_e64 v106, 1.0, v106, s[16:17]
	v_cndmask_b32_e64 v107, 1.0, v107, s[16:17]
; #define LAS __attribute__((address_space(3)))
; #define MFMA16(a, b, c) __builtin_amdgcn_mfma_f32_16x16x32_bf16((a), (b), (c), 0, 0, 0)
; template <int DIR>
; __device__ __forceinline__ void rnn_scan_unit(const Params& p, LAS unsigned char* lds, int b, int g) {
;     ...
;           for (int n = 0; n < 4; ++n) { const int c4 = 16 * n + 4 * fq;
;               f32x4 ra = *(const LAS f32x4*)(cst + c4), ia = *(const LAS f32x4*)(cst + 64 + c4);
; #pragma unroll
;               for (int ks = 0; ks < 2; ++ks) { ra = MFMA16(wreg[(0 * 4 + n) * 2 + ks], af[ks], ra); ia = MFMA16(wl[((1 * 4 + n) * 2 + ks) * 64 + lane], af[ks], ia); }
;               const f32x4 xv = *(const LAS f32x4*)(xcf + tt * XS + c4);
;               const f32x4 spv = *(const LAS f32x4*)(cst + 128 + c4);
;               f32x4 av, bv;
; #pragma unroll
;               for (int i = 0; i < 4; ++i) { const float r = __builtin_amdgcn_rcpf(1.0f + __builtin_amdgcn_exp2f(ra[i])), ig = __builtin_amdgcn_rcpf(1.0f + __builtin_amdgcn_exp2f(ia[i]));
;                   const float a = __builtin_amdgcn_exp2f(r * spv[i]); const float em = fmaf(-a, a, 1.0f);
;                   av[i] = valid ? a : 1.0f; bv[i] = valid ? __builtin_amdgcn_sqrtf(fmaxf(em, 0.0f)) * ig * xv[i] : 0.0f; }
;               *(LAS f32x4*)(al + tt * 64 + c4) = av; *(LAS f32x4*)(bl + tt * 64 + c4) = bv; } }
.Lgate_nomask_6:
	ds_write_b128 v130, v[104:107] offset:6848
	ds_write_b128 v130, v[112:115] offset:10944
	ds_read_b128 v[96:99], v134
	ds_read_b128 v[100:103], v135
	ds_read_b128 v[104:107], v117 offset:12288
	s_waitcnt lgkmcnt(2)
	v_mfma_f32_16x16x32_bf16 v[96:99], v[60:63], v[88:91], v[96:99]
	v_mov_b32_e32 v113, 0
	v_mov_b32_e32 v112, 0
	s_waitcnt lgkmcnt(0)
	v_mfma_f32_16x16x32_bf16 v[100:103], v[104:107], v[88:91], v[100:103]
	v_mfma_f32_16x16x32_bf16 v[104:107], v[64:67], v[92:95], v[96:99]
	s_nop 2
	ds_read_b128 v[96:99], v117 offset:13312
	s_waitcnt lgkmcnt(0)
	v_mfma_f32_16x16x32_bf16 v[96:99], v[96:99], v[92:95], v[100:103]
	s_nop 1
	ds_read_b128 v[100:103], v128 offset:2560
	ds_read_b128 v[108:111], v136
	v_exp_f32_e32 v104, v104
	v_exp_f32_e32 v105, v105
	v_exp_f32_e32 v106, v106
	v_exp_f32_e32 v107, v107
	v_exp_f32_e32 v96, v96
	v_exp_f32_e32 v97, v97
	v_exp_f32_e32 v98, v98
	v_exp_f32_e32 v99, v99
	v_add_f32_e32 v104, 1.0, v104
	v_add_f32_e32 v105, 1.0, v105
	v_add_f32_e32 v106, 1.0, v106
	v_add_f32_e32 v107, 1.0, v107
	v_add_f32_e32 v96, 1.0, v96
	v_add_f32_e32 v97, 1.0, v97
	v_add_f32_e32 v98, 1.0, v98
	v_add_f32_e32 v99, 1.0, v99
	v_rcp_f32_e32 v104, v104
	v_rcp_f32_e32 v105, v105
	v_rcp_f32_e32 v106, v106
	v_rcp_f32_e32 v107, v107
	v_rcp_f32_e32 v96, v96
	v_rcp_f32_e32 v97, v97
	v_rcp_f32_e32 v98, v98
	v_rcp_f32_e32 v99, v99
	s_waitcnt lgkmcnt(0)
	v_mul_f32_e32 v104, v104, v108
	v_mul_f32_e32 v105, v105, v109
	v_mul_f32_e32 v106, v106, v110
	v_mul_f32_e32 v107, v107, v111
	v_exp_f32_e32 v104, v104
	v_exp_f32_e32 v105, v105
	v_exp_f32_e32 v106, v106
	v_exp_f32_e32 v107, v107
	v_fma_f32 v112, -v104, v104, 1.0
	v_fma_f32 v113, -v105, v105, 1.0
	v_fma_f32 v114, -v106, v106, 1.0
	v_fma_f32 v115, -v107, v107, 1.0
	v_max_f32_e32 v112, 0, v112
	v_max_f32_e32 v113, 0, v113
	v_max_f32_e32 v114, 0, v114
	v_max_f32_e32 v115, 0, v115
	v_sqrt_f32_e32 v112, v112
	v_sqrt_f32_e32 v113, v113
	v_sqrt_f32_e32 v114, v114
	v_sqrt_f32_e32 v115, v115
	v_mul_f32_e32 v96, v96, v112
	v_mul_f32_e32 v97, v97, v113
	v_mul_f32_e32 v98, v98, v114
	v_mul_f32_e32 v99, v99, v115
	v_mul_f32_e32 v112, v100, v96
	v_mul_f32_e32 v113, v101, v97
	v_mul_f32_e32 v114, v102, v98
	v_mul_f32_e32 v115, v103, v99
	s_cmp_eq_u64 s[16:17], exec
	s_cbranch_scc1 .Lgate_nomask_5
	v_cndmask_b32_e64 v112, 0, v112, s[16:17]
	v_cndmask_b32_e64 v113, 0, v113, s[16:17]
	v_cndmask_b32_e64 v114, 0, v114, s[16:17]
	v_cndmask_b32_e64 v115, 0, v115, s[16:17]
	v_cndmask_b32_e64 v104, 1.0, v104, s[16:17]
	v_cndmask_b32_e64 v105, 1.0, v105, s[16:17]
	v_cndmask_b32_e64 v106, 1.0, v106, s[16:17]
	v_cndmask_b32_e64 v107, 1.0, v107, s[16:17]
.Lgate_nomask_5:
	ds_write_b128 v130, v[104:107] offset:6912
	ds_write_b128 v130, v[112:115] offset:11008
	ds_read_b128 v[96:99], v137
	ds_read_b128 v[100:103], v138
	ds_read_b128 v[104:107], v117 offset:14336
	s_waitcnt lgkmcnt(2)
	v_mfma_f32_16x16x32_bf16 v[96:99], v[68:71], v[88:91], v[96:99]
	s_waitcnt lgkmcnt(0)
	v_mfma_f32_16x16x32_bf16 v[88:91], v[104:107], v[88:91], v[100:103]
	v_mov_b32_e32 v105, 0
	s_nop 1
	ds_read_b128 v[100:103], v117 offset:15360
	v_mov_b32_e32 v104, 0
	v_mfma_f32_16x16x32_bf16 v[96:99], v[72:75], v[92:95], v[96:99]
	s_waitcnt lgkmcnt(0)
	v_mfma_f32_16x16x32_bf16 v[88:91], v[100:103], v[92:95], v[88:91]
	ds_read_b128 v[92:95], v128 offset:2624
	ds_read_b128 v[100:103], v139
	s_nop 3
	v_exp_f32_e32 v96, v96
	v_exp_f32_e32 v97, v97
	v_exp_f32_e32 v98, v98
	v_exp_f32_e32 v99, v99
	v_exp_f32_e32 v88, v88
	v_exp_f32_e32 v89, v89
	v_exp_f32_e32 v90, v90
	v_exp_f32_e32 v91, v91
	v_add_f32_e32 v96, 1.0, v96
	v_add_f32_e32 v97, 1.0, v97
	v_add_f32_e32 v98, 1.0, v98
	v_add_f32_e32 v99, 1.0, v99
	v_add_f32_e32 v88, 1.0, v88
	v_add_f32_e32 v89, 1.0, v89
	v_add_f32_e32 v90, 1.0, v90
	v_add_f32_e32 v91, 1.0, v91
	v_rcp_f32_e32 v96, v96
	v_rcp_f32_e32 v97, v97
	v_rcp_f32_e32 v98, v98
	v_rcp_f32_e32 v99, v99
	v_rcp_f32_e32 v88, v88
	v_rcp_f32_e32 v89, v89
	v_rcp_f32_e32 v90, v90
	v_rcp_f32_e32 v91, v91
	s_waitcnt lgkmcnt(0)
	v_mul_f32_e32 v96, v96, v100
	v_mul_f32_e32 v97, v97, v101
	v_mul_f32_e32 v98, v98, v102
	v_mul_f32_e32 v99, v99, v103
	v_exp_f32_e32 v96, v96
	v_exp_f32_e32 v97, v97
	v_exp_f32_e32 v98, v98
	v_exp_f32_e32 v99, v99
	v_fma_f32 v104, -v96, v96, 1.0
	v_fma_f32 v105, -v97, v97, 1.0
	v_fma_f32 v106, -v98, v98, 1.0
	v_fma_f32 v107, -v99, v99, 1.0
	v_max_f32_e32 v104, 0, v104
	v_max_f32_e32 v105, 0, v105
	v_max_f32_e32 v106, 0, v106
	v_max_f32_e32 v107, 0, v107
	v_sqrt_f32_e32 v104, v104
	v_sqrt_f32_e32 v105, v105
	v_sqrt_f32_e32 v106, v106
	v_sqrt_f32_e32 v107, v107
	v_mul_f32_e32 v88, v88, v104
	v_mul_f32_e32 v89, v89, v105
	v_mul_f32_e32 v90, v90, v106
	v_mul_f32_e32 v91, v91, v107
	v_mul_f32_e32 v104, v92, v88
	v_mul_f32_e32 v105, v93, v89
	v_mul_f32_e32 v106, v94, v90
	v_mul_f32_e32 v107, v95, v91
	s_cmp_eq_u64 s[16:17], exec
	s_cbranch_scc1 .Lgate_nomask_4
	v_cndmask_b32_e64 v104, 0, v104, s[16:17]
	v_cndmask_b32_e64 v105, 0, v105, s[16:17]
	v_cndmask_b32_e64 v106, 0, v106, s[16:17]
	v_cndmask_b32_e64 v107, 0, v107, s[16:17]
	v_cndmask_b32_e64 v96, 1.0, v96, s[16:17]
	v_cndmask_b32_e64 v97, 1.0, v97, s[16:17]
	v_cndmask_b32_e64 v98, 1.0, v98, s[16:17]
	v_cndmask_b32_e64 v99, 1.0, v99, s[16:17]
; #define LAS __attribute__((address_space(3)))
; __device__ __forceinline__ unsigned cvt_pk(float lo, float hi) { unsigned r; asm("v_cvt_pk_bf16_f32 %0, %1, %2" : "=v"(r) : "v"(lo), "v"(hi)); return r; }
; #define LDS_BARRIER() asm volatile("s_waitcnt lgkmcnt(0)\n\ts_barrier" ::: "memory")
; template <int DIR>
; __device__ __forceinline__ void rnn_scan_unit(const Params& p, LAS unsigned char* lds, int b, int g) {
;     ...
;               *(LAS f32x4*)(al + tt * 64 + c4) = av; *(LAS f32x4*)(bl + tt * 64 + c4) = bv; } }
;         asm volatile("s_waitcnt lgkmcnt(0)" ::: "memory");
;         LAS float* sgA = sg + (ci & 1) * 1024; LAS float* sgB = sgA + 512;
;         float av_[16], bv_[16];
;         { float A = 1.f, B = 0.f;
; #pragma unroll
;           for (int k = 0; k < 16; ++k) { const int tt = DIR == 0 ? k : 15 - k; av_[k] = al[tt * 64 + ch]; bv_[k] = bl[tt * 64 + ch]; B = av_[k] * B + bv_[k]; A *= av_[k]; }
;           sgA[seg * 64 + ch] = A; sgB[seg * 64 + ch] = B; }
;         LDS_BARRIER();
;         float h = hcar, hin = hcar;
; #pragma unroll
;         for (int s = 0; s < 8; ++s) { const int sx = DIR == 0 ? s : 7 - s; hin = (sx == seg) ? h : hin; h = sgA[sx * 64 + ch] * h + sgB[sx * 64 + ch]; }
;         hcar = h;
; #pragma unroll
;         for (int k = 0; k < 16; ++k) { const int tt = DIR == 0 ? k : 15 - k; hin = av_[k] * hin + bv_[k]; bl[tt * 64 + ch] = hin; }
;         asm volatile("s_waitcnt lgkmcnt(0)" ::: "memory");
;         { const int tk = lane >> 2, cq4 = lane & 3;
;           if (t0 + tk < TT) { const LAS float* src = bl + tk * 64 + 16 * cq4;
;               const f32x4 x0 = *(const LAS f32x4*)(src), x1 = *(const LAS f32x4*)(src + 4), x2 = *(const LAS f32x4*)(src + 8), x3 = *(const LAS f32x4*)(src + 12);
;               u32x4 w0, w1; w0.x = cvt_pk(x0[0], x0[1]); w0.y = cvt_pk(x0[2], x0[3]); w0.z = cvt_pk(x1[0], x1[1]); w0.w = cvt_pk(x1[2], x1[3]);
;               w1.x = cvt_pk(x2[0], x2[1]); w1.y = cvt_pk(x2[2], x2[3]); w1.z = cvt_pk(x3[0], x3[1]); w1.w = cvt_pk(x3[2], x3[3]);
;               bf16_t* hp = H + ((size_t)b * TT + t0 + tk) * 512 + 64 * g + 16 * cq4;
;               *(u32x4*)hp = w0; *(u32x4*)(hp + 8) = w1; } }
;         asm volatile("s_waitcnt lgkmcnt(0)" ::: "memory");
.Lgate_nomask_4:
	ds_write_b128 v130, v[96:99] offset:6976
	ds_write_b128 v130, v[104:107] offset:11072
	s_waitcnt lgkmcnt(0)
	v_add_u32_e32 v169, 0x80, v154
	ds_read2st64_b32 v[88:89], v169 offset0:41 offset1:42
	ds_read2st64_b32 v[90:91], v169 offset0:55 offset1:57
	v_add_u32_e32 v3, 0x80, v155
	ds_read2st64_b32 v[92:93], v3 offset0:41 offset1:57
	ds_read2st64_b32 v[94:95], v169 offset0:38 offset1:39
	ds_read2st64_b32 v[172:173], v169 offset0:43 offset1:44
	ds_read2st64_b32 v[98:99], v169 offset0:36 offset1:37
	ds_read2st64_b32 v[102:103], v169 offset0:34 offset1:35
	ds_read2st64_b32 v[96:97], v169 offset0:53 offset1:54
	s_waitcnt lgkmcnt(6)
	v_fma_f32 v0, 0, v88, v91
	ds_read2st64_b32 v[100:101], v169 offset0:51 offset1:52
	ds_read2st64_b32 v[104:105], v169 offset0:49 offset1:50
	ds_read2st64_b32 v[108:109], v169 offset0:47 offset1:48
	ds_read2st64_b32 v[114:115], v169 offset0:45 offset1:46
	s_waitcnt lgkmcnt(9)
	v_fma_f32 v0, v0, v92, v93
	v_mul_f32_e32 v3, v88, v92
	s_waitcnt lgkmcnt(8)
	v_fma_f32 v0, v0, v95, v90
	v_mul_f32_e32 v3, v3, v95
	s_waitcnt lgkmcnt(4)
	v_fma_f32 v0, v0, v94, v97
	v_mul_f32_e32 v3, v3, v94
	ds_read2st64_b32 v[106:107], v169 offset0:32 offset1:33
	ds_read2st64_b32 v[112:113], v169 offset0:30 offset1:31
	ds_read2st64_b32 v[170:171], v169 offset0:28 offset1:29
	ds_read2st64_b32 v[174:175], v169 offset0:26 offset1:27
	v_fma_f32 v0, v0, v99, v96
	v_mul_f32_e32 v3, v3, v99
	s_waitcnt lgkmcnt(7)
	v_fma_f32 v0, v0, v98, v101
	v_mul_f32_e32 v3, v3, v98
	v_fma_f32 v0, v0, v103, v100
	v_mul_f32_e32 v3, v3, v103
	s_waitcnt lgkmcnt(6)
	v_fma_f32 v0, v0, v102, v105
	v_mul_f32_e32 v3, v3, v102
	s_waitcnt lgkmcnt(3)
	v_fma_f32 v0, v0, v107, v104
	v_mul_f32_e32 v3, v3, v107
	v_fma_f32 v0, v0, v106, v109
	v_mul_f32_e32 v3, v3, v106
	s_waitcnt lgkmcnt(2)
	v_fma_f32 v0, v0, v113, v108
	v_mul_f32_e32 v3, v3, v113
	s_and_b32 s16, s34, 0x400
	v_fma_f32 v0, v0, v112, v115
	v_mul_f32_e32 v3, v3, v112
	s_lshl_b32 s16, s16, 2
	s_waitcnt lgkmcnt(1)
	v_fma_f32 v0, v0, v171, v114
	v_mul_f32_e32 v3, v3, v171
	s_add_i32 s16, s16, 0
	v_fma_f32 v0, v0, v170, v173
	v_mul_f32_e32 v3, v3, v170
	s_add_i32 s16, s16, 0x1d400
	s_waitcnt lgkmcnt(0)
	v_fma_f32 v0, v0, v175, v172
	v_mul_f32_e32 v3, v3, v175
	v_fma_f32 v0, v0, v174, v89
	v_mul_f32_e32 v3, v3, v174
	v_lshl_add_u32 v110, v116, 2, s16
	ds_write2st64_b32 v110, v3, v0 offset1:8
	s_waitcnt lgkmcnt(0)
	s_barrier
	v_lshl_add_u32 v0, v122, 2, s16
	ds_read2st64_b32 v[110:111], v0 offset0:6 offset1:7
	ds_read2st64_b32 v[176:177], v0 offset0:14 offset1:15
	s_waitcnt lgkmcnt(0)
	v_fma_f32 v3, v2, v111, v177
	v_cndmask_b32_e64 v2, v2, v3, s[0:1]
	v_fmac_f32_e32 v176, v3, v110
	v_cndmask_b32_e64 v177, v2, v176, s[2:3]
	ds_read2st64_b32 v[2:3], v0 offset0:4 offset1:5
	ds_read2st64_b32 v[110:111], v0 offset0:12 offset1:13
	s_waitcnt lgkmcnt(0)
	v_fma_f32 v3, v176, v3, v111
	v_cndmask_b32_e64 v111, v177, v3, s[4:5]
	v_fmac_f32_e32 v110, v3, v2
	ds_read2st64_b32 v[2:3], v0 offset0:2 offset1:3
	ds_read2st64_b32 v[176:177], v0 offset0:10 offset1:11
	v_cndmask_b32_e64 v111, v111, v110, s[8:9]
	s_waitcnt lgkmcnt(0)
	v_fma_f32 v3, v110, v3, v177
	v_cndmask_b32_e64 v110, v111, v3, s[10:11]
	v_fmac_f32_e32 v176, v3, v2
	v_cndmask_b32_e64 v177, v110, v176, s[12:13]
	ds_read2st64_b32 v[110:111], v0 offset1:1
	ds_read2st64_b32 v[2:3], v0 offset0:8 offset1:9
	s_waitcnt lgkmcnt(0)
	v_fma_f32 v0, v176, v111, v3
	v_cndmask_b32_e64 v3, v177, v0, s[14:15]
	v_fma_f32 v3, v88, v3, v91
	v_fmac_f32_e32 v93, v92, v3
	v_fmac_f32_e32 v90, v95, v93
	ds_write_b32 v154, v3 offset:14720
	v_fma_f32 v3, v94, v90, v97
	v_fmac_f32_e32 v96, v99, v3
	ds_write2st64_b32 v169, v3, v90 offset0:54 offset1:55
	v_fma_f32 v3, v98, v96, v101
	v_fmac_f32_e32 v100, v103, v3
	ds_write2st64_b32 v169, v3, v96 offset0:52 offset1:53
	v_fma_f32 v3, v102, v100, v105
	v_fmac_f32_e32 v104, v107, v3
	ds_write2st64_b32 v169, v3, v100 offset0:50 offset1:51
	v_fma_f32 v3, v106, v104, v109
	v_fmac_f32_e32 v108, v113, v3
	ds_write2st64_b32 v169, v3, v104 offset0:48 offset1:49
	v_fma_f32 v3, v112, v108, v115
	v_fmac_f32_e32 v114, v171, v3
	ds_write2st64_b32 v169, v3, v108 offset0:46 offset1:47
	v_fma_f32 v3, v170, v114, v173
	v_fmac_f32_e32 v172, v175, v3
	v_fmac_f32_e32 v89, v174, v172
	ds_write_b32 v155, v93 offset:14720
	ds_write2st64_b32 v169, v3, v114 offset0:44 offset1:45
	ds_write2st64_b32 v169, v89, v172 offset0:42 offset1:43
	s_waitcnt lgkmcnt(0)
	v_add_u32_e32 v3, s19, v159
	v_cmp_gt_i32_e64 s[16:17], s86, v3
	s_and_saveexec_b64 s[76:77], s[16:17]
	s_cbranch_execz .LBB0_539
	ds_read_b128 v[88:91], v124 offset:10880
	ds_read_b128 v[92:95], v124 offset:10896
	ds_read_b128 v[96:99], v124 offset:10912
	ds_read_b128 v[100:103], v124 offset:10928
	s_waitcnt lgkmcnt(3)
	v_cvt_pk_bf16_f32 v88, v88, v89
	v_cvt_pk_bf16_f32 v89, v90, v91
	s_waitcnt lgkmcnt(2)
	v_cvt_pk_bf16_f32 v90, v92, v93
	v_cvt_pk_bf16_f32 v91, v94, v95
	s_waitcnt lgkmcnt(1)
	v_cvt_pk_bf16_f32 v92, v96, v97
	v_cvt_pk_bf16_f32 v93, v98, v99
	s_waitcnt lgkmcnt(0)
	v_cvt_pk_bf16_f32 v94, v100, v101
	v_cvt_pk_bf16_f32 v95, v102, v103
	global_store_dwordx4 v[120:121], v[88:91], off
	global_store_dwordx4 v[120:121], v[92:95], off offset:16
	s_branch .LBB0_539

; #define LAS __attribute__((address_space(3)))
; __device__ __forceinline__ unsigned cvt_pk(float lo, float hi) { unsigned r; asm("v_cvt_pk_bf16_f32 %0, %1, %2" : "=v"(r) : "v"(lo), "v"(hi)); return r; }
; __device__ __forceinline__ float bflo(unsigned w) { return __uint_as_float(w << 16); }
; __device__ __forceinline__ float bfhi(unsigned w) { return __uint_as_float(w & 0xffff0000u); }
; #define MFMA16(a, b, c) __builtin_amdgcn_mfma_f32_16x16x32_bf16((a), (b), (c), 0, 0, 0)
; template <int DIR>
; __device__ __forceinline__ void rnn_scan_unit(const Params& p, LAS unsigned char* lds, int b, int g) {
;     ...
;         { const int tl0 = lane >> 3, c8 = lane & 7;
; #pragma unroll
;           for (int hh = 0; hh < 2; ++hh) { const int tl = tl0 + 8 * hh;
;               f32x4 o0 = cbv[0], o1 = cbv[1];
; #pragma unroll
;               for (int j = 0; j < 4; ++j) { const u32x4 xw_ = *(const LAS u32x4*)(xrb + (tl + j) * 64 + 8 * c8);
;                   o0[0] += cwv[j][0][0] * bflo(xw_.x); o0[1] += cwv[j][0][1] * bfhi(xw_.x); o0[2] += cwv[j][0][2] * bflo(xw_.y); o0[3] += cwv[j][0][3] * bfhi(xw_.y);
;                   o1[0] += cwv[j][1][0] * bflo(xw_.z); o1[1] += cwv[j][1][1] * bfhi(xw_.z); o1[2] += cwv[j][1][2] * bflo(xw_.w); o1[3] += cwv[j][1][3] * bfhi(xw_.w); }
;               *(LAS f32x4*)(xcf + tl * XS + 8 * c8) = o0; *(LAS f32x4*)(xcf + tl * XS + 8 * c8 + 4) = o1; } }
;         asm volatile("s_waitcnt lgkmcnt(0)" ::: "memory");
;         { const int tt = fr; const bool valid = (t0 + tt) < TT;
;           bf16x8 af[2];
; #pragma unroll
;           for (int ks = 0; ks < 2; ++ks) { const f32x4 x0 = *(const LAS f32x4*)(xcf + tt * XS + 32 * ks + 8 * fq), x1 = *(const LAS f32x4*)(xcf + tt * XS + 32 * ks + 8 * fq + 4);
;               u32x4 w; w.x = cvt_pk(x0[0], x0[1]); w.y = cvt_pk(x0[2], x0[3]); w.z = cvt_pk(x1[0], x1[1]); w.w = cvt_pk(x1[2], x1[3]); af[ks] = __builtin_bit_cast(bf16x8, w); }
; #pragma unroll
;           for (int n = 0; n < 4; ++n) { const int c4 = 16 * n + 4 * fq;
;               f32x4 ra = *(const LAS f32x4*)(cst + c4), ia = *(const LAS f32x4*)(cst + 64 + c4);
; #pragma unroll
;               for (int ks = 0; ks < 2; ++ks) { ra = MFMA16(wreg[(0 * 4 + n) * 2 + ks], af[ks], ra); ia = MFMA16(wl[((1 * 4 + n) * 2 + ks) * 64 + lane], af[ks], ia); }
.LBB0_606:
	v_add_u32_e32 v0, v123, v126
	ds_read_b128 v[88:91], v0
	ds_read_b128 v[92:95], v0 offset:128
	ds_read_b128 v[96:99], v0 offset:256
	ds_read_b128 v[100:103], v0 offset:384
	v_mov_b32_e32 v113, 0
	s_waitcnt lgkmcnt(3)
	v_lshlrev_b32_e32 v104, 16, v88
	v_and_b32_e32 v105, 0xffff0000, v88
	v_lshlrev_b32_e32 v88, 16, v89
	v_and_b32_e32 v89, 0xffff0000, v89
	v_pk_fma_f32 v[104:105], v[36:37], v[104:105], v[40:41]
	s_waitcnt lgkmcnt(2)
	v_lshlrev_b32_e32 v106, 16, v92
	v_and_b32_e32 v107, 0xffff0000, v92
	v_pk_fma_f32 v[88:89], v[38:39], v[88:89], v[42:43]
	v_lshlrev_b32_e32 v92, 16, v93
	v_and_b32_e32 v93, 0xffff0000, v93
	v_pk_fma_f32 v[104:105], v[8:9], v[106:107], v[104:105]
	s_waitcnt lgkmcnt(1)
	v_lshlrev_b32_e32 v106, 16, v96
	v_and_b32_e32 v107, 0xffff0000, v96
	v_pk_fma_f32 v[88:89], v[10:11], v[92:93], v[88:89]
	v_lshlrev_b32_e32 v92, 16, v97
	v_and_b32_e32 v93, 0xffff0000, v97
	v_pk_fma_f32 v[104:105], v[12:13], v[106:107], v[104:105]
	s_waitcnt lgkmcnt(0)
	v_lshlrev_b32_e32 v106, 16, v100
	v_and_b32_e32 v107, 0xffff0000, v100
	v_pk_fma_f32 v[88:89], v[14:15], v[92:93], v[88:89]
	v_lshlrev_b32_e32 v92, 16, v101
	v_and_b32_e32 v93, 0xffff0000, v101
	v_pk_fma_f32 v[104:105], v[20:21], v[106:107], v[104:105]
	v_pk_fma_f32 v[106:107], v[22:23], v[92:93], v[88:89]
	v_lshlrev_b32_e32 v88, 16, v90
	v_and_b32_e32 v89, 0xffff0000, v90
	v_pk_fma_f32 v[88:89], v[28:29], v[88:89], v[32:33]
	v_lshlrev_b32_e32 v92, 16, v94
	v_and_b32_e32 v93, 0xffff0000, v94
	v_pk_fma_f32 v[88:89], v[4:5], v[92:93], v[88:89]
	v_lshlrev_b32_e32 v92, 16, v98
	v_and_b32_e32 v93, 0xffff0000, v98
	v_pk_fma_f32 v[88:89], v[16:17], v[92:93], v[88:89]
	v_lshlrev_b32_e32 v92, 16, v102
	v_and_b32_e32 v93, 0xffff0000, v102
	v_lshlrev_b32_e32 v90, 16, v91
	v_and_b32_e32 v91, 0xffff0000, v91
	v_pk_fma_f32 v[88:89], v[24:25], v[92:93], v[88:89]
	v_pk_fma_f32 v[90:91], v[30:31], v[90:91], v[34:35]
	v_lshlrev_b32_e32 v92, 16, v95
	v_and_b32_e32 v93, 0xffff0000, v95
	v_pk_fma_f32 v[90:91], v[6:7], v[92:93], v[90:91]
	v_lshlrev_b32_e32 v92, 16, v99
	v_and_b32_e32 v93, 0xffff0000, v99
	v_pk_fma_f32 v[90:91], v[18:19], v[92:93], v[90:91]
	v_lshlrev_b32_e32 v92, 16, v103
	v_and_b32_e32 v93, 0xffff0000, v103
	v_pk_fma_f32 v[90:91], v[26:27], v[92:93], v[90:91]
	ds_write_b128 v165, v[104:107] offset:2432
	ds_write_b128 v165, v[88:91] offset:2448
	ds_read_b128 v[88:91], v166
	ds_read_b128 v[92:95], v0 offset:1152
	ds_read_b128 v[96:99], v0 offset:1280
	ds_read_b128 v[100:103], v0 offset:1408
	v_add_u32_e32 v0, s19, v159
	s_waitcnt lgkmcnt(3)
	v_lshlrev_b32_e32 v104, 16, v88
	v_and_b32_e32 v105, 0xffff0000, v88
	v_lshlrev_b32_e32 v88, 16, v89
	v_and_b32_e32 v89, 0xffff0000, v89
	v_pk_fma_f32 v[104:105], v[36:37], v[104:105], v[40:41]
	s_waitcnt lgkmcnt(2)
	v_lshlrev_b32_e32 v106, 16, v92
	v_and_b32_e32 v107, 0xffff0000, v92
	v_pk_fma_f32 v[88:89], v[38:39], v[88:89], v[42:43]
	v_lshlrev_b32_e32 v92, 16, v93
	v_and_b32_e32 v93, 0xffff0000, v93
	v_pk_fma_f32 v[104:105], v[8:9], v[106:107], v[104:105]
	s_waitcnt lgkmcnt(1)
	v_lshlrev_b32_e32 v106, 16, v96
	v_and_b32_e32 v107, 0xffff0000, v96
	v_pk_fma_f32 v[88:89], v[10:11], v[92:93], v[88:89]
	v_lshlrev_b32_e32 v92, 16, v97
	v_and_b32_e32 v93, 0xffff0000, v97
	v_pk_fma_f32 v[104:105], v[12:13], v[106:107], v[104:105]
	s_waitcnt lgkmcnt(0)
	v_lshlrev_b32_e32 v106, 16, v100
	v_and_b32_e32 v107, 0xffff0000, v100
	v_pk_fma_f32 v[88:89], v[14:15], v[92:93], v[88:89]
	v_lshlrev_b32_e32 v92, 16, v101
	v_and_b32_e32 v93, 0xffff0000, v101
	v_pk_fma_f32 v[104:105], v[20:21], v[106:107], v[104:105]
	v_pk_fma_f32 v[106:107], v[22:23], v[92:93], v[88:89]
	v_lshlrev_b32_e32 v88, 16, v90
	v_and_b32_e32 v89, 0xffff0000, v90
	v_pk_fma_f32 v[88:89], v[28:29], v[88:89], v[32:33]
	v_lshlrev_b32_e32 v92, 16, v94
	v_and_b32_e32 v93, 0xffff0000, v94
	v_pk_fma_f32 v[88:89], v[4:5], v[92:93], v[88:89]
	v_lshlrev_b32_e32 v92, 16, v98
	v_and_b32_e32 v93, 0xffff0000, v98
	v_pk_fma_f32 v[88:89], v[16:17], v[92:93], v[88:89]
	v_lshlrev_b32_e32 v92, 16, v102
	v_and_b32_e32 v93, 0xffff0000, v102
	v_lshlrev_b32_e32 v90, 16, v91
	v_and_b32_e32 v91, 0xffff0000, v91
	v_pk_fma_f32 v[88:89], v[24:25], v[92:93], v[88:89]
	v_pk_fma_f32 v[90:91], v[30:31], v[90:91], v[34:35]
	v_lshlrev_b32_e32 v92, 16, v95
	v_and_b32_e32 v93, 0xffff0000, v95
	v_pk_fma_f32 v[90:91], v[6:7], v[92:93], v[90:91]
	v_lshlrev_b32_e32 v92, 16, v99
	v_and_b32_e32 v93, 0xffff0000, v99
	v_pk_fma_f32 v[90:91], v[18:19], v[92:93], v[90:91]
	v_lshlrev_b32_e32 v92, 16, v103
	v_and_b32_e32 v93, 0xffff0000, v103
	v_pk_fma_f32 v[90:91], v[26:27], v[92:93], v[90:91]
	ds_write_b128 v165, v[104:107] offset:4608
	ds_write_b128 v165, v[88:91] offset:4624
	s_waitcnt lgkmcnt(0)
	ds_read_b128 v[88:91], v167 offset:2432
	ds_read_b128 v[92:95], v167 offset:2448
	s_waitcnt lgkmcnt(1)
	v_cvt_pk_bf16_f32 v88, v88, v89
	v_cvt_pk_bf16_f32 v89, v90, v91
	s_waitcnt lgkmcnt(0)
	v_cvt_pk_bf16_f32 v90, v92, v93
	v_cvt_pk_bf16_f32 v91, v94, v95
	ds_read_b128 v[92:95], v167 offset:2560
	ds_read_b128 v[96:99], v167 offset:2576
	s_waitcnt lgkmcnt(1)
	v_cvt_pk_bf16_f32 v92, v92, v93
	v_cvt_pk_bf16_f32 v93, v94, v95
	s_waitcnt lgkmcnt(0)
	v_cvt_pk_bf16_f32 v94, v96, v97
	v_cvt_pk_bf16_f32 v95, v98, v99
	ds_read_b128 v[96:99], v127
	ds_read_b128 v[100:103], v128
	ds_read_b128 v[104:107], v122 offset:8192
	s_waitcnt lgkmcnt(2)
	v_mfma_f32_16x16x32_bf16 v[96:99], v[44:47], v[88:91], v[96:99]
	v_cmp_gt_i32_e64 s[16:17], s86, v0
	v_mov_b32_e32 v112, 0
	s_waitcnt lgkmcnt(0)
	v_mfma_f32_16x16x32_bf16 v[100:103], v[104:107], v[88:91], v[100:103]
	v_mfma_f32_16x16x32_bf16 v[104:107], v[48:51], v[92:95], v[96:99]
	s_nop 2
	ds_read_b128 v[96:99], v122 offset:9216
	s_waitcnt lgkmcnt(0)
; #define LAS __attribute__((address_space(3)))
; #define MFMA16(a, b, c) __builtin_amdgcn_mfma_f32_16x16x32_bf16((a), (b), (c), 0, 0, 0)
; template <int DIR>
; __device__ __forceinline__ void rnn_scan_unit(const Params& p, LAS unsigned char* lds, int b, int g) {
;     ...
;           for (int n = 0; n < 4; ++n) { const int c4 = 16 * n + 4 * fq;
;               f32x4 ra = *(const LAS f32x4*)(cst + c4), ia = *(const LAS f32x4*)(cst + 64 + c4);
; #pragma unroll
;               for (int ks = 0; ks < 2; ++ks) { ra = MFMA16(wreg[(0 * 4 + n) * 2 + ks], af[ks], ra); ia = MFMA16(wl[((1 * 4 + n) * 2 + ks) * 64 + lane], af[ks], ia); }
;               const f32x4 xv = *(const LAS f32x4*)(xcf + tt * XS + c4);
;               const f32x4 spv = *(const LAS f32x4*)(cst + 128 + c4);
;               f32x4 av, bv;
; #pragma unroll
;               for (int i = 0; i < 4; ++i) { const float r = __builtin_amdgcn_rcpf(1.0f + __builtin_amdgcn_exp2f(ra[i])), ig = __builtin_amdgcn_rcpf(1.0f + __builtin_amdgcn_exp2f(ia[i]));
;                   const float a = __builtin_amdgcn_exp2f(r * spv[i]); const float em = fmaf(-a, a, 1.0f);
;                   av[i] = valid ? a : 1.0f; bv[i] = valid ? __builtin_amdgcn_sqrtf(fmaxf(em, 0.0f)) * ig * xv[i] : 0.0f; }
;               *(LAS f32x4*)(al + tt * 64 + c4) = av; *(LAS f32x4*)(bl + tt * 64 + c4) = bv; } }
	v_mfma_f32_16x16x32_bf16 v[100:103], v[96:99], v[92:95], v[100:103]
	s_nop 1
	ds_read_b128 v[96:99], v129 offset:2432
	ds_read_b128 v[108:111], v130
	v_exp_f32_e32 v104, v104
	v_exp_f32_e32 v105, v105
	v_exp_f32_e32 v106, v106
	v_exp_f32_e32 v107, v107
	v_exp_f32_e32 v100, v100
	v_exp_f32_e32 v101, v101
	v_exp_f32_e32 v102, v102
	v_exp_f32_e32 v103, v103
	v_add_f32_e32 v104, 1.0, v104
	v_add_f32_e32 v105, 1.0, v105
	v_add_f32_e32 v106, 1.0, v106
	v_add_f32_e32 v107, 1.0, v107
	v_add_f32_e32 v100, 1.0, v100
	v_add_f32_e32 v101, 1.0, v101
	v_add_f32_e32 v102, 1.0, v102
	v_add_f32_e32 v103, 1.0, v103
	v_rcp_f32_e32 v104, v104
	v_rcp_f32_e32 v105, v105
	v_rcp_f32_e32 v106, v106
	v_rcp_f32_e32 v107, v107
	v_rcp_f32_e32 v100, v100
	v_rcp_f32_e32 v101, v101
	v_rcp_f32_e32 v102, v102
	v_rcp_f32_e32 v103, v103
	s_waitcnt lgkmcnt(0)
	v_mul_f32_e32 v104, v104, v108
	v_mul_f32_e32 v105, v105, v109
	v_mul_f32_e32 v106, v106, v110
	v_mul_f32_e32 v107, v107, v111
	v_exp_f32_e32 v104, v104
	v_exp_f32_e32 v105, v105
	v_exp_f32_e32 v106, v106
	v_exp_f32_e32 v107, v107
	v_fma_f32 v112, -v104, v104, 1.0
	v_fma_f32 v113, -v105, v105, 1.0
	v_fma_f32 v114, -v106, v106, 1.0
	v_fma_f32 v115, -v107, v107, 1.0
	v_max_f32_e32 v112, 0, v112
	v_max_f32_e32 v113, 0, v113
	v_max_f32_e32 v114, 0, v114
	v_max_f32_e32 v115, 0, v115
	v_sqrt_f32_e32 v112, v112
	v_sqrt_f32_e32 v113, v113
	v_sqrt_f32_e32 v114, v114
	v_sqrt_f32_e32 v115, v115
	v_mul_f32_e32 v100, v100, v112
	v_mul_f32_e32 v101, v101, v113
	v_mul_f32_e32 v102, v102, v114
	v_mul_f32_e32 v103, v103, v115
	v_mul_f32_e32 v112, v96, v100
	v_mul_f32_e32 v113, v97, v101
	v_mul_f32_e32 v114, v98, v102
	v_mul_f32_e32 v115, v99, v103
	s_cmp_eq_u64 s[16:17], exec
	s_cbranch_scc1 .Lgate_nomask_3
	v_cndmask_b32_e64 v112, 0, v112, s[16:17]
	v_cndmask_b32_e64 v113, 0, v113, s[16:17]
	v_cndmask_b32_e64 v114, 0, v114, s[16:17]
	v_cndmask_b32_e64 v115, 0, v115, s[16:17]
	v_cndmask_b32_e64 v104, 1.0, v104, s[16:17]
	v_cndmask_b32_e64 v105, 1.0, v105, s[16:17]
	v_cndmask_b32_e64 v106, 1.0, v106, s[16:17]
	v_cndmask_b32_e64 v107, 1.0, v107, s[16:17]
.Lgate_nomask_3:
	ds_write_b128 v131, v[104:107] offset:6784
	ds_write_b128 v131, v[112:115] offset:10880
	ds_read_b128 v[96:99], v132
	ds_read_b128 v[100:103], v133
	ds_read_b128 v[104:107], v122 offset:10240
	s_waitcnt lgkmcnt(2)
	v_mfma_f32_16x16x32_bf16 v[96:99], v[52:55], v[88:91], v[96:99]
	v_mov_b32_e32 v113, 0
	v_mov_b32_e32 v112, 0
	s_waitcnt lgkmcnt(0)
	v_mfma_f32_16x16x32_bf16 v[100:103], v[104:107], v[88:91], v[100:103]
	v_mfma_f32_16x16x32_bf16 v[104:107], v[56:59], v[92:95], v[96:99]
	s_nop 2
	ds_read_b128 v[96:99], v122 offset:11264
	s_waitcnt lgkmcnt(0)
	v_mfma_f32_16x16x32_bf16 v[96:99], v[96:99], v[92:95], v[100:103]
	s_nop 1
	ds_read_b128 v[100:103], v129 offset:2496
	ds_read_b128 v[108:111], v134
	v_exp_f32_e32 v104, v104
	v_exp_f32_e32 v105, v105
	v_exp_f32_e32 v106, v106
	v_exp_f32_e32 v107, v107
	v_exp_f32_e32 v96, v96
	v_exp_f32_e32 v97, v97
	v_exp_f32_e32 v98, v98
	v_exp_f32_e32 v99, v99
	v_add_f32_e32 v104, 1.0, v104
	v_add_f32_e32 v105, 1.0, v105
	v_add_f32_e32 v106, 1.0, v106
	v_add_f32_e32 v107, 1.0, v107
	v_add_f32_e32 v96, 1.0, v96
	v_add_f32_e32 v97, 1.0, v97
	v_add_f32_e32 v98, 1.0, v98
	v_add_f32_e32 v99, 1.0, v99
	v_rcp_f32_e32 v104, v104
	v_rcp_f32_e32 v105, v105
	v_rcp_f32_e32 v106, v106
	v_rcp_f32_e32 v107, v107
	v_rcp_f32_e32 v96, v96
	v_rcp_f32_e32 v97, v97
	v_rcp_f32_e32 v98, v98
	v_rcp_f32_e32 v99, v99
	s_waitcnt lgkmcnt(0)
	v_mul_f32_e32 v104, v104, v108
	v_mul_f32_e32 v105, v105, v109
	v_mul_f32_e32 v106, v106, v110
	v_mul_f32_e32 v107, v107, v111
	v_exp_f32_e32 v104, v104
	v_exp_f32_e32 v105, v105
	v_exp_f32_e32 v106, v106
	v_exp_f32_e32 v107, v107
	v_fma_f32 v112, -v104, v104, 1.0
	v_fma_f32 v113, -v105, v105, 1.0
	v_fma_f32 v114, -v106, v106, 1.0
	v_fma_f32 v115, -v107, v107, 1.0
	v_max_f32_e32 v112, 0, v112
	v_max_f32_e32 v113, 0, v113
	v_max_f32_e32 v114, 0, v114
	v_max_f32_e32 v115, 0, v115
	v_sqrt_f32_e32 v112, v112
	v_sqrt_f32_e32 v113, v113
	v_sqrt_f32_e32 v114, v114
	v_sqrt_f32_e32 v115, v115
	v_mul_f32_e32 v96, v96, v112
	v_mul_f32_e32 v97, v97, v113
	v_mul_f32_e32 v98, v98, v114
	v_mul_f32_e32 v99, v99, v115
	v_mul_f32_e32 v112, v100, v96
	v_mul_f32_e32 v113, v101, v97
	v_mul_f32_e32 v114, v102, v98
	v_mul_f32_e32 v115, v103, v99
	s_cmp_eq_u64 s[16:17], exec
	s_cbranch_scc1 .Lgate_nomask_2
	v_cndmask_b32_e64 v112, 0, v112, s[16:17]
	v_cndmask_b32_e64 v113, 0, v113, s[16:17]
	v_cndmask_b32_e64 v114, 0, v114, s[16:17]
	v_cndmask_b32_e64 v115, 0, v115, s[16:17]
	v_cndmask_b32_e64 v104, 1.0, v104, s[16:17]
	v_cndmask_b32_e64 v105, 1.0, v105, s[16:17]
	v_cndmask_b32_e64 v106, 1.0, v106, s[16:17]
	v_cndmask_b32_e64 v107, 1.0, v107, s[16:17]
; #define LAS __attribute__((address_space(3)))
; #define MFMA16(a, b, c) __builtin_amdgcn_mfma_f32_16x16x32_bf16((a), (b), (c), 0, 0, 0)
; template <int DIR>
; __device__ __forceinline__ void rnn_scan_unit(const Params& p, LAS unsigned char* lds, int b, int g) {
;     ...
;           for (int n = 0; n < 4; ++n) { const int c4 = 16 * n + 4 * fq;
;               f32x4 ra = *(const LAS f32x4*)(cst + c4), ia = *(const LAS f32x4*)(cst + 64 + c4);
; #pragma unroll
;               for (int ks = 0; ks < 2; ++ks) { ra = MFMA16(wreg[(0 * 4 + n) * 2 + ks], af[ks], ra); ia = MFMA16(wl[((1 * 4 + n) * 2 + ks) * 64 + lane], af[ks], ia); }
;               const f32x4 xv = *(const LAS f32x4*)(xcf + tt * XS + c4);
;               const f32x4 spv = *(const LAS f32x4*)(cst + 128 + c4);
;               f32x4 av, bv;
; #pragma unroll
;               for (int i = 0; i < 4; ++i) { const float r = __builtin_amdgcn_rcpf(1.0f + __builtin_amdgcn_exp2f(ra[i])), ig = __builtin_amdgcn_rcpf(1.0f + __builtin_amdgcn_exp2f(ia[i]));
;                   const float a = __builtin_amdgcn_exp2f(r * spv[i]); const float em = fmaf(-a, a, 1.0f);
;                   av[i] = valid ? a : 1.0f; bv[i] = valid ? __builtin_amdgcn_sqrtf(fmaxf(em, 0.0f)) * ig * xv[i] : 0.0f; }
;               *(LAS f32x4*)(al + tt * 64 + c4) = av; *(LAS f32x4*)(bl + tt * 64 + c4) = bv; } }
.Lgate_nomask_2:
	ds_write_b128 v131, v[104:107] offset:6848
	ds_write_b128 v131, v[112:115] offset:10944
	ds_read_b128 v[96:99], v135
	ds_read_b128 v[100:103], v136
	ds_read_b128 v[104:107], v122 offset:12288
	s_waitcnt lgkmcnt(2)
	v_mfma_f32_16x16x32_bf16 v[96:99], v[60:63], v[88:91], v[96:99]
	v_mov_b32_e32 v113, 0
	v_mov_b32_e32 v112, 0
	s_waitcnt lgkmcnt(0)
	v_mfma_f32_16x16x32_bf16 v[100:103], v[104:107], v[88:91], v[100:103]
	v_mfma_f32_16x16x32_bf16 v[104:107], v[64:67], v[92:95], v[96:99]
	s_nop 2
	ds_read_b128 v[96:99], v122 offset:13312
	s_waitcnt lgkmcnt(0)
	v_mfma_f32_16x16x32_bf16 v[96:99], v[96:99], v[92:95], v[100:103]
	s_nop 1
	ds_read_b128 v[100:103], v129 offset:2560
	ds_read_b128 v[108:111], v137
	v_exp_f32_e32 v104, v104
	v_exp_f32_e32 v105, v105
	v_exp_f32_e32 v106, v106
	v_exp_f32_e32 v107, v107
	v_exp_f32_e32 v96, v96
	v_exp_f32_e32 v97, v97
	v_exp_f32_e32 v98, v98
	v_exp_f32_e32 v99, v99
	v_add_f32_e32 v104, 1.0, v104
	v_add_f32_e32 v105, 1.0, v105
	v_add_f32_e32 v106, 1.0, v106
	v_add_f32_e32 v107, 1.0, v107
	v_add_f32_e32 v96, 1.0, v96
	v_add_f32_e32 v97, 1.0, v97
	v_add_f32_e32 v98, 1.0, v98
	v_add_f32_e32 v99, 1.0, v99
	v_rcp_f32_e32 v104, v104
	v_rcp_f32_e32 v105, v105
	v_rcp_f32_e32 v106, v106
	v_rcp_f32_e32 v107, v107
	v_rcp_f32_e32 v96, v96
	v_rcp_f32_e32 v97, v97
	v_rcp_f32_e32 v98, v98
	v_rcp_f32_e32 v99, v99
	s_waitcnt lgkmcnt(0)
	v_mul_f32_e32 v104, v104, v108
	v_mul_f32_e32 v105, v105, v109
	v_mul_f32_e32 v106, v106, v110
	v_mul_f32_e32 v107, v107, v111
	v_exp_f32_e32 v104, v104
	v_exp_f32_e32 v105, v105
	v_exp_f32_e32 v106, v106
	v_exp_f32_e32 v107, v107
	v_fma_f32 v112, -v104, v104, 1.0
	v_fma_f32 v113, -v105, v105, 1.0
	v_fma_f32 v114, -v106, v106, 1.0
	v_fma_f32 v115, -v107, v107, 1.0
	v_max_f32_e32 v112, 0, v112
	v_max_f32_e32 v113, 0, v113
	v_max_f32_e32 v114, 0, v114
	v_max_f32_e32 v115, 0, v115
	v_sqrt_f32_e32 v112, v112
	v_sqrt_f32_e32 v113, v113
	v_sqrt_f32_e32 v114, v114
	v_sqrt_f32_e32 v115, v115
	v_mul_f32_e32 v96, v96, v112
	v_mul_f32_e32 v97, v97, v113
	v_mul_f32_e32 v98, v98, v114
	v_mul_f32_e32 v99, v99, v115
	v_mul_f32_e32 v112, v100, v96
	v_mul_f32_e32 v113, v101, v97
	v_mul_f32_e32 v114, v102, v98
	v_mul_f32_e32 v115, v103, v99
	s_cmp_eq_u64 s[16:17], exec
	s_cbranch_scc1 .Lgate_nomask_1
	v_cndmask_b32_e64 v112, 0, v112, s[16:17]
	v_cndmask_b32_e64 v113, 0, v113, s[16:17]
	v_cndmask_b32_e64 v114, 0, v114, s[16:17]
	v_cndmask_b32_e64 v115, 0, v115, s[16:17]
	v_cndmask_b32_e64 v104, 1.0, v104, s[16:17]
	v_cndmask_b32_e64 v105, 1.0, v105, s[16:17]
	v_cndmask_b32_e64 v106, 1.0, v106, s[16:17]
	v_cndmask_b32_e64 v107, 1.0, v107, s[16:17]
.Lgate_nomask_1:
	ds_write_b128 v131, v[104:107] offset:6912
	ds_write_b128 v131, v[112:115] offset:11008
	ds_read_b128 v[96:99], v138
	ds_read_b128 v[100:103], v139
	ds_read_b128 v[104:107], v122 offset:14336
	s_waitcnt lgkmcnt(2)
	v_mfma_f32_16x16x32_bf16 v[96:99], v[68:71], v[88:91], v[96:99]
	s_waitcnt lgkmcnt(0)
	v_mfma_f32_16x16x32_bf16 v[88:91], v[104:107], v[88:91], v[100:103]
	v_mov_b32_e32 v105, 0
	s_nop 1
	ds_read_b128 v[100:103], v122 offset:15360
	v_mov_b32_e32 v104, 0
	v_mfma_f32_16x16x32_bf16 v[96:99], v[72:75], v[92:95], v[96:99]
	s_waitcnt lgkmcnt(0)
	v_mfma_f32_16x16x32_bf16 v[88:91], v[100:103], v[92:95], v[88:91]
	ds_read_b128 v[92:95], v129 offset:2624
	ds_read_b128 v[100:103], v154
	s_nop 3
	v_exp_f32_e32 v96, v96
	v_exp_f32_e32 v97, v97
	v_exp_f32_e32 v98, v98
	v_exp_f32_e32 v99, v99
	v_exp_f32_e32 v88, v88
	v_exp_f32_e32 v89, v89
	v_exp_f32_e32 v90, v90
	v_exp_f32_e32 v91, v91
	v_add_f32_e32 v96, 1.0, v96
	v_add_f32_e32 v97, 1.0, v97
	v_add_f32_e32 v98, 1.0, v98
	v_add_f32_e32 v99, 1.0, v99
	v_add_f32_e32 v88, 1.0, v88
	v_add_f32_e32 v89, 1.0, v89
	v_add_f32_e32 v90, 1.0, v90
	v_add_f32_e32 v91, 1.0, v91
	v_rcp_f32_e32 v96, v96
	v_rcp_f32_e32 v97, v97
	v_rcp_f32_e32 v98, v98
	v_rcp_f32_e32 v99, v99
	v_rcp_f32_e32 v88, v88
	v_rcp_f32_e32 v89, v89
	v_rcp_f32_e32 v90, v90
	v_rcp_f32_e32 v91, v91
	s_waitcnt lgkmcnt(0)
	v_mul_f32_e32 v96, v96, v100
	v_mul_f32_e32 v97, v97, v101
	v_mul_f32_e32 v98, v98, v102
	v_mul_f32_e32 v99, v99, v103
	v_exp_f32_e32 v96, v96
	v_exp_f32_e32 v97, v97
	v_exp_f32_e32 v98, v98
	v_exp_f32_e32 v99, v99
	v_fma_f32 v104, -v96, v96, 1.0
	v_fma_f32 v105, -v97, v97, 1.0
	v_fma_f32 v106, -v98, v98, 1.0
	v_fma_f32 v107, -v99, v99, 1.0
	v_max_f32_e32 v104, 0, v104
	v_max_f32_e32 v105, 0, v105
	v_max_f32_e32 v106, 0, v106
	v_max_f32_e32 v107, 0, v107
	v_sqrt_f32_e32 v104, v104
	v_sqrt_f32_e32 v105, v105
	v_sqrt_f32_e32 v106, v106
	v_sqrt_f32_e32 v107, v107
	v_mul_f32_e32 v88, v88, v104
	v_mul_f32_e32 v89, v89, v105
	v_mul_f32_e32 v90, v90, v106
	v_mul_f32_e32 v91, v91, v107
	v_mul_f32_e32 v104, v92, v88
	v_mul_f32_e32 v105, v93, v89
	v_mul_f32_e32 v106, v94, v90
	v_mul_f32_e32 v107, v95, v91
	s_cmp_eq_u64 s[16:17], exec
	s_cbranch_scc1 .Lgate_nomask_0
	v_cndmask_b32_e64 v104, 0, v104, s[16:17]
	v_cndmask_b32_e64 v105, 0, v105, s[16:17]
	v_cndmask_b32_e64 v106, 0, v106, s[16:17]
	v_cndmask_b32_e64 v107, 0, v107, s[16:17]
	v_cndmask_b32_e64 v96, 1.0, v96, s[16:17]
	v_cndmask_b32_e64 v97, 1.0, v97, s[16:17]
	v_cndmask_b32_e64 v98, 1.0, v98, s[16:17]
	v_cndmask_b32_e64 v99, 1.0, v99, s[16:17]
; #define LAS __attribute__((address_space(3)))
; __device__ __forceinline__ unsigned cvt_pk(float lo, float hi) { unsigned r; asm("v_cvt_pk_bf16_f32 %0, %1, %2" : "=v"(r) : "v"(lo), "v"(hi)); return r; }
; #define LDS_BARRIER() asm volatile("s_waitcnt lgkmcnt(0)\n\ts_barrier" ::: "memory")
; template <int DIR>
; __device__ __forceinline__ void rnn_scan_unit(const Params& p, LAS unsigned char* lds, int b, int g) {
;     ...
;               *(LAS f32x4*)(al + tt * 64 + c4) = av; *(LAS f32x4*)(bl + tt * 64 + c4) = bv; } }
;         asm volatile("s_waitcnt lgkmcnt(0)" ::: "memory");
;         LAS float* sgA = sg + (ci & 1) * 1024; LAS float* sgB = sgA + 512;
;         float av_[16], bv_[16];
;         { float A = 1.f, B = 0.f;
; #pragma unroll
;           for (int k = 0; k < 16; ++k) { const int tt = DIR == 0 ? k : 15 - k; av_[k] = al[tt * 64 + ch]; bv_[k] = bl[tt * 64 + ch]; B = av_[k] * B + bv_[k]; A *= av_[k]; }
;           sgA[seg * 64 + ch] = A; sgB[seg * 64 + ch] = B; }
;         LDS_BARRIER();
;         float h = hcar, hin = hcar;
; #pragma unroll
;         for (int s = 0; s < 8; ++s) { const int sx = DIR == 0 ? s : 7 - s; hin = (sx == seg) ? h : hin; h = sgA[sx * 64 + ch] * h + sgB[sx * 64 + ch]; }
;         hcar = h;
; #pragma unroll
;         for (int k = 0; k < 16; ++k) { const int tt = DIR == 0 ? k : 15 - k; hin = av_[k] * hin + bv_[k]; bl[tt * 64 + ch] = hin; }
;         asm volatile("s_waitcnt lgkmcnt(0)" ::: "memory");
;         { const int tk = lane >> 2, cq4 = lane & 3;
;           if (t0 + tk < TT) { const LAS float* src = bl + tk * 64 + 16 * cq4;
;               const f32x4 x0 = *(const LAS f32x4*)(src), x1 = *(const LAS f32x4*)(src + 4), x2 = *(const LAS f32x4*)(src + 8), x3 = *(const LAS f32x4*)(src + 12);
;               u32x4 w0, w1; w0.x = cvt_pk(x0[0], x0[1]); w0.y = cvt_pk(x0[2], x0[3]); w0.z = cvt_pk(x1[0], x1[1]); w0.w = cvt_pk(x1[2], x1[3]);
;               w1.x = cvt_pk(x2[0], x2[1]); w1.y = cvt_pk(x2[2], x2[3]); w1.z = cvt_pk(x3[0], x3[1]); w1.w = cvt_pk(x3[2], x3[3]);
;               bf16_t* hp = H + ((size_t)b * TT + t0 + tk) * 512 + 64 * g + 16 * cq4;
;               *(u32x4*)hp = w0; *(u32x4*)(hp + 8) = w1; } }
;         asm volatile("s_waitcnt lgkmcnt(0)" ::: "memory");
.Lgate_nomask_0:
	ds_write_b128 v131, v[96:99] offset:6976
	ds_write_b128 v131, v[104:107] offset:11072
	s_waitcnt lgkmcnt(0)
	v_add_u32_e32 v176, 0x80, v124
	ds_read2st64_b32 v[88:89], v176 offset0:26 offset1:27
	ds_read2st64_b32 v[90:91], v176 offset0:42 offset1:43
	ds_read2st64_b32 v[94:95], v176 offset0:28 offset1:29
	ds_read2st64_b32 v[92:93], v176 offset0:44 offset1:45
	ds_read2st64_b32 v[98:99], v176 offset0:30 offset1:31
	ds_read2st64_b32 v[96:97], v176 offset0:46 offset1:47
	ds_read2st64_b32 v[100:101], v176 offset0:32 offset1:33
	ds_read2st64_b32 v[102:103], v176 offset0:48 offset1:49
	s_waitcnt lgkmcnt(7)
	v_mul_f32_e32 v2, v88, v89
	s_waitcnt lgkmcnt(6)
	v_fma_f32 v0, 0, v88, v90
	v_fma_f32 v0, v0, v89, v91
	s_waitcnt lgkmcnt(4)
	v_fma_f32 v0, v0, v94, v92
	v_mul_f32_e32 v2, v2, v94
	v_fma_f32 v0, v0, v95, v93
	v_mul_f32_e32 v2, v2, v95
	ds_read2st64_b32 v[104:105], v176 offset0:34 offset1:35
	ds_read2st64_b32 v[106:107], v176 offset0:50 offset1:51
	s_waitcnt lgkmcnt(4)
	v_fma_f32 v0, v0, v98, v96
	v_mul_f32_e32 v2, v2, v98
	v_fma_f32 v0, v0, v99, v97
	v_mul_f32_e32 v2, v2, v99
	ds_read2st64_b32 v[110:111], v176 offset0:36 offset1:37
	ds_read2st64_b32 v[108:109], v176 offset0:52 offset1:53
	s_waitcnt lgkmcnt(4)
	v_fma_f32 v0, v0, v100, v102
	v_mul_f32_e32 v2, v2, v100
	v_fma_f32 v0, v0, v101, v103
	v_mul_f32_e32 v2, v2, v101
	ds_read2st64_b32 v[114:115], v176 offset0:38 offset1:39
	ds_read2st64_b32 v[168:169], v176 offset0:54 offset1:55
	s_waitcnt lgkmcnt(4)
	v_fma_f32 v0, v0, v104, v106
	v_mul_f32_e32 v2, v2, v104
	v_fma_f32 v0, v0, v105, v107
	v_mul_f32_e32 v2, v2, v105
	ds_read2st64_b32 v[170:171], v176 offset0:40 offset1:41
	ds_read2st64_b32 v[172:173], v176 offset0:56 offset1:57
	s_waitcnt lgkmcnt(4)
	v_fma_f32 v0, v0, v110, v108
	v_mul_f32_e32 v2, v2, v110
	s_and_b32 s16, s34, 0x400
	v_fma_f32 v0, v0, v111, v109
	v_mul_f32_e32 v2, v2, v111
	s_lshl_b32 s16, s16, 2
	s_waitcnt lgkmcnt(2)
	v_fma_f32 v0, v0, v114, v168
	v_mul_f32_e32 v2, v2, v114
	s_add_i32 s16, s16, 0
	v_fma_f32 v0, v0, v115, v169
	v_mul_f32_e32 v2, v2, v115
	s_add_i32 s16, s16, 0x1d400
	s_waitcnt lgkmcnt(0)
	v_fma_f32 v0, v0, v170, v172
	v_mul_f32_e32 v2, v2, v170
	v_fma_f32 v0, v0, v171, v173
	v_mul_f32_e32 v2, v2, v171
	v_lshl_add_u32 v112, v120, 2, s16
	ds_write2st64_b32 v112, v2, v0 offset1:8
	s_waitcnt lgkmcnt(0)
	s_barrier
	v_lshl_add_u32 v0, v121, 2, s16
	ds_read2st64_b32 v[112:113], v0 offset1:1
	ds_read2st64_b32 v[174:175], v0 offset0:8 offset1:9
	s_waitcnt lgkmcnt(0)
	v_fma_f32 v2, v3, v112, v174
	v_cndmask_b32_e64 v3, v3, v2, s[0:1]
	v_fmac_f32_e32 v175, v2, v113
	v_cndmask_b32_e64 v174, v3, v175, s[2:3]
	ds_read2st64_b32 v[2:3], v0 offset0:2 offset1:3
	ds_read2st64_b32 v[112:113], v0 offset0:10 offset1:11
	s_waitcnt lgkmcnt(0)
	v_fma_f32 v2, v175, v2, v112
	v_cndmask_b32_e64 v112, v174, v2, s[4:5]
	v_fmac_f32_e32 v113, v2, v3
	ds_read2st64_b32 v[2:3], v0 offset0:4 offset1:5
	ds_read2st64_b32 v[174:175], v0 offset0:12 offset1:13
	v_cndmask_b32_e64 v112, v112, v113, s[8:9]
	s_waitcnt lgkmcnt(0)
	v_fma_f32 v2, v113, v2, v174
	v_cndmask_b32_e64 v112, v112, v2, s[10:11]
	v_fmac_f32_e32 v175, v2, v3
	v_cndmask_b32_e64 v174, v112, v175, s[12:13]
	ds_read2st64_b32 v[112:113], v0 offset0:6 offset1:7
	ds_read2st64_b32 v[2:3], v0 offset0:14 offset1:15
	s_waitcnt lgkmcnt(0)
	v_fma_f32 v0, v175, v112, v2
	v_cndmask_b32_e64 v2, v174, v0, s[14:15]
	v_fma_f32 v2, v88, v2, v90
	v_fmac_f32_e32 v91, v89, v2
	ds_write2st64_b32 v176, v2, v91 offset0:42 offset1:43
	v_fma_f32 v2, v94, v91, v92
	v_fmac_f32_e32 v93, v95, v2
	ds_write2st64_b32 v176, v2, v93 offset0:44 offset1:45
	v_fma_f32 v2, v98, v93, v96
	v_fmac_f32_e32 v97, v99, v2
	ds_write2st64_b32 v176, v2, v97 offset0:46 offset1:47
	v_fma_f32 v2, v100, v97, v102
	v_fmac_f32_e32 v103, v101, v2
	ds_write2st64_b32 v176, v2, v103 offset0:48 offset1:49
	v_fma_f32 v2, v104, v103, v106
	v_fmac_f32_e32 v107, v105, v2
	ds_write2st64_b32 v176, v2, v107 offset0:50 offset1:51
	v_fma_f32 v2, v110, v107, v108
	v_fmac_f32_e32 v109, v111, v2
	ds_write2st64_b32 v176, v2, v109 offset0:52 offset1:53
	v_fma_f32 v2, v114, v109, v168
	v_fmac_f32_e32 v169, v115, v2
	ds_write2st64_b32 v176, v2, v169 offset0:54 offset1:55
	v_fma_f32 v2, v170, v169, v172
	v_fmac_f32_e32 v173, v171, v2
	ds_write2st64_b32 v176, v2, v173 offset0:56 offset1:57
	s_waitcnt lgkmcnt(0)
	v_add_u32_e32 v2, s19, v158
	v_cmp_gt_i32_e64 s[16:17], s86, v2
	s_and_saveexec_b64 s[76:77], s[16:17]
	s_cbranch_execz .LBB0_595
	ds_read_b128 v[88:91], v125 offset:10880
	ds_read_b128 v[92:95], v125 offset:10896
	ds_read_b128 v[96:99], v125 offset:10912
	ds_read_b128 v[100:103], v125 offset:10928
	s_waitcnt lgkmcnt(3)
	v_cvt_pk_bf16_f32 v88, v88, v89
	v_cvt_pk_bf16_f32 v89, v90, v91
	s_waitcnt lgkmcnt(2)
	v_cvt_pk_bf16_f32 v90, v92, v93
	v_cvt_pk_bf16_f32 v91, v94, v95
	s_waitcnt lgkmcnt(1)
	v_cvt_pk_bf16_f32 v92, v96, v97
	v_cvt_pk_bf16_f32 v93, v98, v99
	s_waitcnt lgkmcnt(0)
	v_cvt_pk_bf16_f32 v94, v100, v101
	v_cvt_pk_bf16_f32 v95, v102, v103
	global_store_dwordx4 v[118:119], v[88:91], off
	global_store_dwordx4 v[118:119], v[92:95], off offset:16
	s_branch .LBB0_595
